# v110 minus two dead VALU adds (unused stage-write bases) in the differential-attention tile loop
# baseline (speedup 1.0000x reference)
.Ldf_loop:
	s_bitcmp1_b32 s72, 0
	s_cselect_b32 s46, 0x12800, 0
	s_xor_b32 s12, s46, 0x12800
	v_add_u32_e32 v230, s46, v181
	ds_read_b128 v[194:197], v230 offset:0
	ds_read_b128 v[198:201], v230 offset:32
	ds_read_b128 v[202:205], v230 offset:64
	ds_read_b128 v[206:209], v230 offset:96
	v_mfma_f32_32x32x16_bf16 v[50:65], v[210:213], v[134:137], v[50:65]
	ds_read_b128 v[210:213], v230 offset:8704
	v_add_u32_e32 v231, s46, v185
	v_add_u32_e32 v232, 0x8800, v231
	v_mfma_f32_32x32x16_bf16 v[66:81], v[214:217], v[134:137], v[66:81]
	ds_read_b128 v[214:217], v230 offset:8736
	v_mfma_f32_32x32x16_bf16 v[34:49], v[218:221], v[134:137], v[34:49]
	ds_read_b128 v[218:221], v230 offset:8768
	v_mfma_f32_32x32x16_bf16 v[18:33], v[226:229], v[134:137], v[18:33]
	ds_read_b128 v[226:229], v230 offset:8800
